# plus: K-loop priority flips moved outside the MFMA segments (before entry barrier / after exit barrier), mid-segment flip pair removed
# speedup vs baseline: 1.0219x; 1.0016x over previous
; #define PG8_STAGE(bufoff, gbase, off, q) do { \
;         __builtin_amdgcn_global_load_lds((const unsigned*)((const char*)(gbase) + (off)), (LAS unsigned*)(lds + (bufoff) + ldsw), 16, 0, 0); \
;         __builtin_amdgcn_global_load_lds((const unsigned*)((const char*)(gbase) + (q) + (off)), (LAS unsigned*)(lds + (bufoff) + ldsw + 8192), 16, 0, 0); } while (0)
; #define PG8_LDA(dst, b, h) do { _Pragma("unroll") for (int m = 0; m < 4; ++m) _Pragma("unroll") for (int k = 0; k < 2; ++k) dst[m][k] = *(const LAS bf16x8*)(lds + PG8_SA(b, h) + aoff + m * 2048 + k * 1024); } while (0)
; #define PG8_LDB(dst, b, h) do { _Pragma("unroll") for (int n = 0; n < 2; ++n) _Pragma("unroll") for (int k = 0; k < 2; ++k) dst[n][k] = *(const LAS bf16x8*)(lds + PG8_SB(b, h) + boff + n * 2048 + k * 1024); } while (0)
; #define PG8_MMA(ai, bj, At, Bt) do { __builtin_amdgcn_s_setprio(1); _Pragma("unroll") for (int m = 0; m < 4; ++m) _Pragma("unroll") for (int n = 0; n < 2; ++n) _Pragma("unroll") for (int k = 0; k < 2; ++k) \
;         acc[ai][bj][m][n] = __builtin_amdgcn_mfma_f32_16x16x32_bf16(Bt[n][k], At[m][k], acc[ai][bj][m][n], 0, 0, 0); __builtin_amdgcn_s_setprio(0); } while (0)
; template <class Epi, class Sched>
; __device__ __forceinline__ void gemm_phase(LAS unsigned char* lds, const int tid, const Sched& S, const Epi& E) {
;     ...
;             const bool last = (t == nt - 2);
;             const char* a1 = cA + (size_t)(t + 1) * kstep;
;             const char* a2 = last ? nA : cA + (size_t)(t + 2) * kstep; const char* b2 = last ? nB : cB + (size_t)(t + 2) * kstep;
;             const char* a3 = a2 + kstep; const char* b3 = b2 + kstep;
;             const unsigned oA2 = last ? noffA : offA, oB2 = last ? noffB : offB;
;             const int qA2 = last ? nqA : qA, qB2 = last ? nqB : qB, hA2 = last ? nhA : hA, hB2 = last ? nhB : hB;
;             PG8_LDB(B0, 0, 0); PG8_LDB(B1, 0, 1); PG8_SCHED; PG8_LDA(At, 0, 0); PG8_STAGE(PG8_SA(1, 1), a1 + hA, offA, qA);
;             PG8_WAIT_V(8); PG8_WAIT_L(0); PG8_BAR; PG8_MMA(0, 0, At, B0); PG8_MMA(0, 1, At, B1); PG8_BAR; PG8_SCHED;
;             PG8_LDA(At, 0, 1); PG8_STAGE(PG8_SB(0, 0), b2, oB2, qB2); PG8_STAGE(PG8_SB(0, 1), b2 + hB2, oB2, qB2); PG8_STAGE(PG8_SA(0, 0), a2, oA2, qA2);
;             PG8_WAIT_V(8); PG8_WAIT_L(0); PG8_BAR; PG8_MMA(1, 0, At, B0); PG8_MMA(1, 1, At, B1); PG8_BAR; PG8_SCHED;
.LBB0_175:
	s_or_b32 vcc_lo, s17, 1
	s_mov_b32 vcc_hi, s21
	s_lshl_b64 s[10:11], vcc, 7
	s_add_u32 s17, s40, s6
	s_addc_u32 vcc_lo, s41, s7
	s_and_b64 s[6:7], exec, s[62:63]
	s_cselect_b32 vcc_hi, s82, vcc_lo
	s_cselect_b32 vcc_lo, s48, s17
	s_add_i32 s17, 0, 0x10000
	v_add_u32_e32 v133, s17, v147
	s_add_i32 s62, 0, 0x14000
	ds_read_b128 v[140:143], v133
	ds_read_b128 v[150:153], v133 offset:1024
	ds_read_b128 v[154:157], v133 offset:2048
	ds_read_b128 v[158:161], v133 offset:3072
	ds_read_b128 v[186:189], v133 offset:16384
	ds_read_b128 v[190:193], v133 offset:17408
	ds_read_b128 v[194:197], v133 offset:18432
	ds_read_b128 v[198:201], v133 offset:19456
	s_add_u32 s6, s68, s10
	s_addc_u32 s7, s16, s11
	s_add_i32 m0, s54, 0xc000
	ds_read_b128 v[202:205], v184
	ds_read_b128 v[206:209], v184 offset:1024
	ds_read_b128 v[210:213], v184 offset:2048
	ds_read_b128 v[214:217], v184 offset:3072
	ds_read_b128 v[218:221], v184 offset:4096
	ds_read_b128 v[222:225], v184 offset:5120
	ds_read_b128 v[226:229], v184 offset:6144
	ds_read_b128 v[230:233], v184 offset:7168
	global_load_lds_dwordx4 v134, s[6:7]
	s_add_u32 s6, s6, s66
	s_addc_u32 s7, s7, s67
	s_add_i32 m0, s54, 0xe000
	s_nop 0
	global_load_lds_dwordx4 v134, s[6:7]
	s_waitcnt vmcnt(8)
	s_waitcnt lgkmcnt(0)
	s_setprio 1
	s_barrier
	v_mfma_f32_16x16x32_bf16 v[126:129], v[140:143], v[202:205], v[126:129]
	v_mfma_f32_16x16x32_bf16 v[122:125], v[154:157], v[202:205], v[122:125]
	v_mfma_f32_16x16x32_bf16 v[110:113], v[140:143], v[210:213], v[110:113]
	v_mfma_f32_16x16x32_bf16 v[106:109], v[154:157], v[210:213], v[106:109]
	v_mfma_f32_16x16x32_bf16 v[94:97], v[140:143], v[218:221], v[94:97]
	v_mfma_f32_16x16x32_bf16 v[90:93], v[154:157], v[218:221], v[90:93]
	v_mfma_f32_16x16x32_bf16 v[78:81], v[140:143], v[226:229], v[78:81]
	v_mfma_f32_16x16x32_bf16 v[74:77], v[154:157], v[226:229], v[74:77]
	v_mfma_f32_16x16x32_bf16 v[126:129], v[150:153], v[206:209], v[126:129]
	v_mfma_f32_16x16x32_bf16 v[122:125], v[158:161], v[206:209], v[122:125]
	v_mfma_f32_16x16x32_bf16 v[110:113], v[150:153], v[214:217], v[110:113]
	v_mfma_f32_16x16x32_bf16 v[106:109], v[158:161], v[214:217], v[106:109]
	v_mfma_f32_16x16x32_bf16 v[94:97], v[150:153], v[222:225], v[94:97]
	v_mfma_f32_16x16x32_bf16 v[90:93], v[158:161], v[222:225], v[90:93]
	v_mfma_f32_16x16x32_bf16 v[78:81], v[150:153], v[230:233], v[78:81]
	v_mfma_f32_16x16x32_bf16 v[74:77], v[158:161], v[230:233], v[74:77]
	v_mfma_f32_16x16x32_bf16 v[118:121], v[186:189], v[202:205], v[118:121]
	v_mfma_f32_16x16x32_bf16 v[114:117], v[194:197], v[202:205], v[114:117]
	v_mfma_f32_16x16x32_bf16 v[102:105], v[186:189], v[210:213], v[102:105]
	v_mfma_f32_16x16x32_bf16 v[98:101], v[194:197], v[210:213], v[98:101]
	v_mfma_f32_16x16x32_bf16 v[86:89], v[186:189], v[218:221], v[86:89]
	v_mfma_f32_16x16x32_bf16 v[82:85], v[194:197], v[218:221], v[82:85]
	v_mfma_f32_16x16x32_bf16 v[70:73], v[186:189], v[226:229], v[70:73]
	v_mfma_f32_16x16x32_bf16 v[66:69], v[194:197], v[226:229], v[66:69]
	v_mfma_f32_16x16x32_bf16 v[118:121], v[190:193], v[206:209], v[118:121]
	v_mfma_f32_16x16x32_bf16 v[114:117], v[198:201], v[206:209], v[114:117]
	v_mfma_f32_16x16x32_bf16 v[102:105], v[190:193], v[214:217], v[102:105]
	v_mfma_f32_16x16x32_bf16 v[98:101], v[198:201], v[214:217], v[98:101]
	v_mfma_f32_16x16x32_bf16 v[86:89], v[190:193], v[222:225], v[86:89]
	v_mfma_f32_16x16x32_bf16 v[82:85], v[198:201], v[222:225], v[82:85]
	v_mfma_f32_16x16x32_bf16 v[70:73], v[190:193], v[230:233], v[70:73]
	v_mfma_f32_16x16x32_bf16 v[66:69], v[198:201], v[230:233], v[66:69]
	s_barrier
	s_setprio 0
	s_add_i32 s10, s17, s47
	s_ashr_i32 s11, s73, 31
	s_mov_b32 m0, s10
	s_add_u32 s6, s28, s73
	ds_read_b128 v[202:205], v184 offset:16384
	ds_read_b128 v[206:209], v184 offset:17408
	ds_read_b128 v[210:213], v184 offset:18432
	ds_read_b128 v[214:217], v184 offset:19456
	ds_read_b128 v[218:221], v184 offset:20480
	ds_read_b128 v[222:225], v184 offset:21504
	ds_read_b128 v[226:229], v184 offset:22528
	ds_read_b128 v[230:233], v184 offset:23552
	global_load_lds_dwordx4 v0, s[28:29]
	s_addc_u32 s7, s29, s11
	s_add_i32 m0, s10, 0x2000
	s_nop 0
	global_load_lds_dwordx4 v0, s[6:7]
	s_ashr_i32 s7, s19, 31
	s_add_u32 s6, s28, s19
	s_addc_u32 s7, s29, s7
	s_add_i32 s10, s62, s47
	s_mov_b32 m0, s10
	s_nop 0
	global_load_lds_dwordx4 v0, s[6:7]
	s_add_u32 s6, s6, s73
	s_addc_u32 s7, s7, s11
	s_add_i32 m0, s10, 0x2000
	s_nop 0
	global_load_lds_dwordx4 v0, s[6:7]
	s_add_u32 s6, vcc_lo, s64
	s_mov_b32 m0, s54
	s_addc_u32 s7, vcc_hi, s65
	global_load_lds_dwordx4 v136, vcc
	s_mov_b32 m0, s55
	s_nop 0
	global_load_lds_dwordx4 v136, s[6:7]
	s_waitcnt vmcnt(8)
	s_waitcnt lgkmcnt(0)
	s_setprio 1
	s_barrier
; #define PG8_STAGE(bufoff, gbase, off, q) do { \
;         __builtin_amdgcn_global_load_lds((const unsigned*)((const char*)(gbase) + (off)), (LAS unsigned*)(lds + (bufoff) + ldsw), 16, 0, 0); \
;         __builtin_amdgcn_global_load_lds((const unsigned*)((const char*)(gbase) + (q) + (off)), (LAS unsigned*)(lds + (bufoff) + ldsw + 8192), 16, 0, 0); } while (0)
; #define PG8_LDA(dst, b, h) do { _Pragma("unroll") for (int m = 0; m < 4; ++m) _Pragma("unroll") for (int k = 0; k < 2; ++k) dst[m][k] = *(const LAS bf16x8*)(lds + PG8_SA(b, h) + aoff + m * 2048 + k * 1024); } while (0)
; #define PG8_LDB(dst, b, h) do { _Pragma("unroll") for (int n = 0; n < 2; ++n) _Pragma("unroll") for (int k = 0; k < 2; ++k) dst[n][k] = *(const LAS bf16x8*)(lds + PG8_SB(b, h) + boff + n * 2048 + k * 1024); } while (0)
; #define PG8_MMA(ai, bj, At, Bt) do { __builtin_amdgcn_s_setprio(1); _Pragma("unroll") for (int m = 0; m < 4; ++m) _Pragma("unroll") for (int n = 0; n < 2; ++n) _Pragma("unroll") for (int k = 0; k < 2; ++k) \
;         acc[ai][bj][m][n] = __builtin_amdgcn_mfma_f32_16x16x32_bf16(Bt[n][k], At[m][k], acc[ai][bj][m][n], 0, 0, 0); __builtin_amdgcn_s_setprio(0); } while (0)
; #define PG8_WAIT_V(n) asm volatile("s_waitcnt vmcnt(" #n ")" ::: "memory")
; #define PG8_WAIT_L(n) asm volatile("s_waitcnt lgkmcnt(" #n ")" ::: "memory")
; #define PG8_BAR __builtin_amdgcn_s_barrier()
; #define PG8_SCHED __builtin_amdgcn_sched_barrier(0)
; template <class Epi, class Sched>
; __device__ __forceinline__ void gemm_phase(LAS unsigned char* lds, const int tid, const Sched& S, const Epi& E) {
;     ...
;             PG8_WAIT_V(8); PG8_WAIT_L(0); PG8_BAR; PG8_MMA(1, 0, At, B0); PG8_MMA(1, 1, At, B1); PG8_BAR; PG8_SCHED;
;             PG8_LDB(B0, 1, 0); PG8_LDB(B1, 1, 1); PG8_SCHED; PG8_LDA(At, 1, 0); PG8_STAGE(PG8_SA(0, 1), a2 + hA2, oA2, qA2);
;             PG8_WAIT_V(8); PG8_WAIT_L(0); PG8_BAR; PG8_MMA(0, 0, At, B0); PG8_MMA(0, 1, At, B1); PG8_BAR; PG8_SCHED;
	v_mfma_f32_16x16x32_bf16 v[62:65], v[140:143], v[202:205], v[62:65]
	v_mfma_f32_16x16x32_bf16 v[58:61], v[154:157], v[202:205], v[58:61]
	v_mfma_f32_16x16x32_bf16 v[46:49], v[140:143], v[210:213], v[46:49]
	v_mfma_f32_16x16x32_bf16 v[42:45], v[154:157], v[210:213], v[42:45]
	v_mfma_f32_16x16x32_bf16 v[30:33], v[140:143], v[218:221], v[30:33]
	v_mfma_f32_16x16x32_bf16 v[26:29], v[154:157], v[218:221], v[26:29]
	v_mfma_f32_16x16x32_bf16 v[14:17], v[140:143], v[226:229], v[14:17]
	v_mfma_f32_16x16x32_bf16 v[10:13], v[154:157], v[226:229], v[10:13]
	v_mfma_f32_16x16x32_bf16 v[62:65], v[150:153], v[206:209], v[62:65]
	v_mfma_f32_16x16x32_bf16 v[58:61], v[158:161], v[206:209], v[58:61]
	v_mfma_f32_16x16x32_bf16 v[46:49], v[150:153], v[214:217], v[46:49]
	v_mfma_f32_16x16x32_bf16 v[42:45], v[158:161], v[214:217], v[42:45]
	v_mfma_f32_16x16x32_bf16 v[30:33], v[150:153], v[222:225], v[30:33]
	v_mfma_f32_16x16x32_bf16 v[26:29], v[158:161], v[222:225], v[26:29]
	v_mfma_f32_16x16x32_bf16 v[14:17], v[150:153], v[230:233], v[14:17]
	v_mfma_f32_16x16x32_bf16 v[10:13], v[158:161], v[230:233], v[10:13]
	v_mfma_f32_16x16x32_bf16 v[54:57], v[186:189], v[202:205], v[54:57]
	v_mfma_f32_16x16x32_bf16 v[50:53], v[194:197], v[202:205], v[50:53]
	v_mfma_f32_16x16x32_bf16 v[38:41], v[186:189], v[210:213], v[38:41]
	v_mfma_f32_16x16x32_bf16 v[34:37], v[194:197], v[210:213], v[34:37]
	v_mfma_f32_16x16x32_bf16 v[22:25], v[186:189], v[218:221], v[22:25]
	v_mfma_f32_16x16x32_bf16 v[18:21], v[194:197], v[218:221], v[18:21]
	v_mfma_f32_16x16x32_bf16 v[6:9], v[186:189], v[226:229], v[6:9]
	v_mfma_f32_16x16x32_bf16 v[2:5], v[194:197], v[226:229], v[2:5]
	v_mfma_f32_16x16x32_bf16 v[54:57], v[190:193], v[206:209], v[54:57]
	v_mfma_f32_16x16x32_bf16 v[50:53], v[198:201], v[206:209], v[50:53]
	v_mfma_f32_16x16x32_bf16 v[38:41], v[190:193], v[214:217], v[38:41]
	v_mfma_f32_16x16x32_bf16 v[34:37], v[198:201], v[214:217], v[34:37]
	v_mfma_f32_16x16x32_bf16 v[22:25], v[190:193], v[222:225], v[22:25]
	v_mfma_f32_16x16x32_bf16 v[18:21], v[198:201], v[222:225], v[18:21]
	v_mfma_f32_16x16x32_bf16 v[6:9], v[190:193], v[230:233], v[6:9]
	v_mfma_f32_16x16x32_bf16 v[2:5], v[198:201], v[230:233], v[2:5]
	s_barrier
	s_setprio 0
	s_add_i32 s10, 0, 0x18000
	s_add_i32 s11, 0, 0x1c000
	ds_read_b128 v[140:143], v133 offset:32768
	ds_read_b128 v[150:153], v133 offset:33792
	ds_read_b128 v[154:157], v133 offset:34816
	ds_read_b128 v[158:161], v133 offset:35840
	ds_read_b128 v[186:189], v133 offset:49152
	ds_read_b128 v[190:193], v133 offset:50176
	ds_read_b128 v[194:197], v133 offset:51200
	ds_read_b128 v[198:201], v133 offset:52224
	s_add_u32 s6, vcc_lo, s58
	s_addc_u32 s7, vcc_hi, s59
	s_mov_b32 m0, s91
	ds_read_b128 v[202:205], v184 offset:32768
	ds_read_b128 v[206:209], v184 offset:33792
	ds_read_b128 v[210:213], v184 offset:34816
	ds_read_b128 v[214:217], v184 offset:35840
	ds_read_b128 v[218:221], v184 offset:36864
	ds_read_b128 v[222:225], v184 offset:37888
	ds_read_b128 v[226:229], v184 offset:38912
	ds_read_b128 v[230:233], v184 offset:39936
	global_load_lds_dwordx4 v136, s[6:7]
	s_add_u32 s6, s6, s64
	s_addc_u32 s7, s7, s65
	s_mov_b32 m0, s93
	s_nop 0
	global_load_lds_dwordx4 v136, s[6:7]
	s_waitcnt vmcnt(8)
	s_waitcnt lgkmcnt(0)
	s_setprio 1
	s_barrier
	v_mfma_f32_16x16x32_bf16 v[126:129], v[140:143], v[202:205], v[126:129]
	v_mfma_f32_16x16x32_bf16 v[122:125], v[154:157], v[202:205], v[122:125]
	v_mfma_f32_16x16x32_bf16 v[110:113], v[140:143], v[210:213], v[110:113]
	v_mfma_f32_16x16x32_bf16 v[106:109], v[154:157], v[210:213], v[106:109]
	v_mfma_f32_16x16x32_bf16 v[94:97], v[140:143], v[218:221], v[94:97]
	v_mfma_f32_16x16x32_bf16 v[90:93], v[154:157], v[218:221], v[90:93]
	v_mfma_f32_16x16x32_bf16 v[78:81], v[140:143], v[226:229], v[78:81]
	v_mfma_f32_16x16x32_bf16 v[74:77], v[154:157], v[226:229], v[74:77]
	v_mfma_f32_16x16x32_bf16 v[126:129], v[150:153], v[206:209], v[126:129]
	v_mfma_f32_16x16x32_bf16 v[122:125], v[158:161], v[206:209], v[122:125]
	v_mfma_f32_16x16x32_bf16 v[110:113], v[150:153], v[214:217], v[110:113]
	v_mfma_f32_16x16x32_bf16 v[106:109], v[158:161], v[214:217], v[106:109]
	v_mfma_f32_16x16x32_bf16 v[94:97], v[150:153], v[222:225], v[94:97]
	v_mfma_f32_16x16x32_bf16 v[90:93], v[158:161], v[222:225], v[90:93]
	v_mfma_f32_16x16x32_bf16 v[78:81], v[150:153], v[230:233], v[78:81]
	v_mfma_f32_16x16x32_bf16 v[74:77], v[158:161], v[230:233], v[74:77]
	v_mfma_f32_16x16x32_bf16 v[118:121], v[186:189], v[202:205], v[118:121]
	v_mfma_f32_16x16x32_bf16 v[114:117], v[194:197], v[202:205], v[114:117]
	v_mfma_f32_16x16x32_bf16 v[102:105], v[186:189], v[210:213], v[102:105]
	v_mfma_f32_16x16x32_bf16 v[98:101], v[194:197], v[210:213], v[98:101]
	v_mfma_f32_16x16x32_bf16 v[86:89], v[186:189], v[218:221], v[86:89]
	v_mfma_f32_16x16x32_bf16 v[82:85], v[194:197], v[218:221], v[82:85]
	v_mfma_f32_16x16x32_bf16 v[70:73], v[186:189], v[226:229], v[70:73]
	v_mfma_f32_16x16x32_bf16 v[66:69], v[194:197], v[226:229], v[66:69]
	v_mfma_f32_16x16x32_bf16 v[118:121], v[190:193], v[206:209], v[118:121]
	v_mfma_f32_16x16x32_bf16 v[114:117], v[198:201], v[206:209], v[114:117]
	v_mfma_f32_16x16x32_bf16 v[102:105], v[190:193], v[214:217], v[102:105]
	v_mfma_f32_16x16x32_bf16 v[98:101], v[198:201], v[214:217], v[98:101]
	v_mfma_f32_16x16x32_bf16 v[86:89], v[190:193], v[222:225], v[86:89]
	v_mfma_f32_16x16x32_bf16 v[82:85], v[198:201], v[222:225], v[82:85]
	v_mfma_f32_16x16x32_bf16 v[70:73], v[190:193], v[230:233], v[70:73]
	v_mfma_f32_16x16x32_bf16 v[66:69], v[198:201], v[230:233], v[66:69]
	s_barrier
; #define PG8_STAGE(bufoff, gbase, off, q) do { \
;         __builtin_amdgcn_global_load_lds((const unsigned*)((const char*)(gbase) + (off)), (LAS unsigned*)(lds + (bufoff) + ldsw), 16, 0, 0); \
;         __builtin_amdgcn_global_load_lds((const unsigned*)((const char*)(gbase) + (q) + (off)), (LAS unsigned*)(lds + (bufoff) + ldsw + 8192), 16, 0, 0); } while (0)
; #define PG8_LDA(dst, b, h) do { _Pragma("unroll") for (int m = 0; m < 4; ++m) _Pragma("unroll") for (int k = 0; k < 2; ++k) dst[m][k] = *(const LAS bf16x8*)(lds + PG8_SA(b, h) + aoff + m * 2048 + k * 1024); } while (0)
; #define PG8_MMA(ai, bj, At, Bt) do { __builtin_amdgcn_s_setprio(1); _Pragma("unroll") for (int m = 0; m < 4; ++m) _Pragma("unroll") for (int n = 0; n < 2; ++n) _Pragma("unroll") for (int k = 0; k < 2; ++k) \
;         acc[ai][bj][m][n] = __builtin_amdgcn_mfma_f32_16x16x32_bf16(Bt[n][k], At[m][k], acc[ai][bj][m][n], 0, 0, 0); __builtin_amdgcn_s_setprio(0); } while (0)
; #define PG8_WAIT_V(n) asm volatile("s_waitcnt vmcnt(" #n ")" ::: "memory")
; #define PG8_WAIT_L(n) asm volatile("s_waitcnt lgkmcnt(" #n ")" ::: "memory")
; #define PG8_BAR __builtin_amdgcn_s_barrier()
; #define PG8_SCHED __builtin_amdgcn_sched_barrier(0)
; template <class Epi, class Sched>
; __device__ __forceinline__ void gemm_phase(LAS unsigned char* lds, const int tid, const Sched& S, const Epi& E) {
;     ...
;             PG8_LDA(At, 1, 1); PG8_STAGE(PG8_SB(1, 0), b3, oB2, qB2); PG8_STAGE(PG8_SB(1, 1), b3 + hB2, oB2, qB2); PG8_STAGE(PG8_SA(1, 0), a3, oA2, qA2);
;             PG8_WAIT_V(8); PG8_WAIT_L(0); PG8_BAR; PG8_MMA(1, 0, At, B0); PG8_MMA(1, 1, At, B1); PG8_BAR; PG8_SCHED;
;         }
	s_setprio 0
	s_add_i32 s6, s10, s47
	s_add_i32 m0, s6, 0xffffff80
	ds_read_b128 v[202:205], v184 offset:49152
	ds_read_b128 v[206:209], v184 offset:50176
	ds_read_b128 v[210:213], v184 offset:51200
	ds_read_b128 v[214:217], v184 offset:52224
	ds_read_b128 v[218:221], v184 offset:53248
	ds_read_b128 v[222:225], v184 offset:54272
	ds_read_b128 v[226:229], v184 offset:55296
	ds_read_b128 v[230:233], v184 offset:56320
	global_load_lds_dwordx4 v0, s[28:29] offset:128
	s_add_i32 m0, s6, 0x1f80
	s_add_i32 s6, s11, s47
	s_ashr_i32 s100, s73, 31
	s_add_u32 s98, s28, s73
	s_addc_u32 s99, s29, s100
	global_load_lds_dwordx4 v0, s[98:99] offset:128
	s_add_i32 m0, s6, 0xffffff80
	s_nop 0
	s_ashr_i32 s101, s19, 31
	s_add_u32 s98, s28, s19
	s_addc_u32 s99, s29, s101
	global_load_lds_dwordx4 v0, s[98:99] offset:128
	s_add_i32 m0, s6, 0x1f80
	s_nop 0
	s_add_u32 s98, s98, s73
	s_addc_u32 s99, s99, s100
	global_load_lds_dwordx4 v0, s[98:99] offset:128
	s_add_i32 m0, s77, 0xffffff80
	s_nop 0
	global_load_lds_dwordx4 v136, vcc offset:128
	s_add_i32 m0, s88, 0xffffff80
	s_nop 0
	s_add_u32 s98, vcc_lo, s64
	s_addc_u32 s99, vcc_hi, s65
	global_load_lds_dwordx4 v136, s[98:99] offset:128
	s_waitcnt vmcnt(8)
	s_waitcnt lgkmcnt(0)
	s_setprio 1
	s_barrier
	v_mfma_f32_16x16x32_bf16 v[62:65], v[140:143], v[202:205], v[62:65]
	v_mfma_f32_16x16x32_bf16 v[58:61], v[154:157], v[202:205], v[58:61]
	v_mfma_f32_16x16x32_bf16 v[46:49], v[140:143], v[210:213], v[46:49]
	v_mfma_f32_16x16x32_bf16 v[42:45], v[154:157], v[210:213], v[42:45]
	v_mfma_f32_16x16x32_bf16 v[30:33], v[140:143], v[218:221], v[30:33]
	v_mfma_f32_16x16x32_bf16 v[26:29], v[154:157], v[218:221], v[26:29]
	v_mfma_f32_16x16x32_bf16 v[14:17], v[140:143], v[226:229], v[14:17]
	v_mfma_f32_16x16x32_bf16 v[10:13], v[154:157], v[226:229], v[10:13]
	v_mfma_f32_16x16x32_bf16 v[62:65], v[150:153], v[206:209], v[62:65]
	v_mfma_f32_16x16x32_bf16 v[58:61], v[158:161], v[206:209], v[58:61]
	v_mfma_f32_16x16x32_bf16 v[46:49], v[150:153], v[214:217], v[46:49]
	v_mfma_f32_16x16x32_bf16 v[42:45], v[158:161], v[214:217], v[42:45]
	v_mfma_f32_16x16x32_bf16 v[30:33], v[150:153], v[222:225], v[30:33]
	v_mfma_f32_16x16x32_bf16 v[26:29], v[158:161], v[222:225], v[26:29]
	v_mfma_f32_16x16x32_bf16 v[14:17], v[150:153], v[230:233], v[14:17]
	v_mfma_f32_16x16x32_bf16 v[10:13], v[158:161], v[230:233], v[10:13]
	v_mfma_f32_16x16x32_bf16 v[54:57], v[186:189], v[202:205], v[54:57]
	v_mfma_f32_16x16x32_bf16 v[50:53], v[194:197], v[202:205], v[50:53]
	v_mfma_f32_16x16x32_bf16 v[38:41], v[186:189], v[210:213], v[38:41]
	v_mfma_f32_16x16x32_bf16 v[34:37], v[194:197], v[210:213], v[34:37]
	v_mfma_f32_16x16x32_bf16 v[22:25], v[186:189], v[218:221], v[22:25]
	v_mfma_f32_16x16x32_bf16 v[18:21], v[194:197], v[218:221], v[18:21]
	v_mfma_f32_16x16x32_bf16 v[6:9], v[186:189], v[226:229], v[6:9]
	v_mfma_f32_16x16x32_bf16 v[2:5], v[194:197], v[226:229], v[2:5]
	v_mfma_f32_16x16x32_bf16 v[54:57], v[190:193], v[206:209], v[54:57]
	v_mfma_f32_16x16x32_bf16 v[50:53], v[198:201], v[206:209], v[50:53]
	v_mfma_f32_16x16x32_bf16 v[38:41], v[190:193], v[214:217], v[38:41]
	v_mfma_f32_16x16x32_bf16 v[34:37], v[198:201], v[214:217], v[34:37]
	v_mfma_f32_16x16x32_bf16 v[22:25], v[190:193], v[222:225], v[22:25]
	v_mfma_f32_16x16x32_bf16 v[18:21], v[198:201], v[222:225], v[18:21]
	v_mfma_f32_16x16x32_bf16 v[6:9], v[190:193], v[230:233], v[6:9]
	v_mfma_f32_16x16x32_bf16 v[2:5], v[198:201], v[230:233], v[2:5]
	s_barrier
	s_setprio 0
	s_cmp_ge_i32 s20, s37
	s_cbranch_scc1 .LBB0_177
	s_mov_b32 s17, s20
	s_branch .LBB0_173

; #define PG8_STAGE(bufoff, gbase, off, q) do { \
;         __builtin_amdgcn_global_load_lds((const unsigned*)((const char*)(gbase) + (off)), (LAS unsigned*)(lds + (bufoff) + ldsw), 16, 0, 0); \
;         __builtin_amdgcn_global_load_lds((const unsigned*)((const char*)(gbase) + (q) + (off)), (LAS unsigned*)(lds + (bufoff) + ldsw + 8192), 16, 0, 0); } while (0)
; #define PG8_LDA(dst, b, h) do { _Pragma("unroll") for (int m = 0; m < 4; ++m) _Pragma("unroll") for (int k = 0; k < 2; ++k) dst[m][k] = *(const LAS bf16x8*)(lds + PG8_SA(b, h) + aoff + m * 2048 + k * 1024); } while (0)
; #define PG8_LDB(dst, b, h) do { _Pragma("unroll") for (int n = 0; n < 2; ++n) _Pragma("unroll") for (int k = 0; k < 2; ++k) dst[n][k] = *(const LAS bf16x8*)(lds + PG8_SB(b, h) + boff + n * 2048 + k * 1024); } while (0)
; #define PG8_MMA(ai, bj, At, Bt) do { __builtin_amdgcn_s_setprio(1); _Pragma("unroll") for (int m = 0; m < 4; ++m) _Pragma("unroll") for (int n = 0; n < 2; ++n) _Pragma("unroll") for (int k = 0; k < 2; ++k) \
;         acc[ai][bj][m][n] = __builtin_amdgcn_mfma_f32_16x16x32_bf16(Bt[n][k], At[m][k], acc[ai][bj][m][n], 0, 0, 0); __builtin_amdgcn_s_setprio(0); } while (0)
; template <class Epi, class Sched>
; __device__ __forceinline__ void gemm_phase(LAS unsigned char* lds, const int tid, const Sched& S, const Epi& E) {
;     ...
;             const bool last = (t == nt - 2);
;             const char* a1 = cA + (size_t)(t + 1) * kstep;
;             const char* a2 = last ? nA : cA + (size_t)(t + 2) * kstep; const char* b2 = last ? nB : cB + (size_t)(t + 2) * kstep;
;             const char* a3 = a2 + kstep; const char* b3 = b2 + kstep;
;             const unsigned oA2 = last ? noffA : offA, oB2 = last ? noffB : offB;
;             const int qA2 = last ? nqA : qA, qB2 = last ? nqB : qB, hA2 = last ? nhA : hA, hB2 = last ? nhB : hB;
;             PG8_LDB(B0, 0, 0); PG8_LDB(B1, 0, 1); PG8_SCHED; PG8_LDA(At, 0, 0); PG8_STAGE(PG8_SA(1, 1), a1 + hA, offA, qA);
;             PG8_WAIT_V(8); PG8_WAIT_L(0); PG8_BAR; PG8_MMA(0, 0, At, B0); PG8_MMA(0, 1, At, B1); PG8_BAR; PG8_SCHED;
;             PG8_LDA(At, 0, 1); PG8_STAGE(PG8_SB(0, 0), b2, oB2, qB2); PG8_STAGE(PG8_SB(0, 1), b2 + hB2, oB2, qB2); PG8_STAGE(PG8_SA(0, 0), a2, oA2, qA2);
;             PG8_WAIT_V(8); PG8_WAIT_L(0); PG8_BAR; PG8_MMA(1, 0, At, B0); PG8_MMA(1, 1, At, B1); PG8_BAR; PG8_SCHED;
.Lk0a_175:
	s_or_b32 vcc_lo, s17, 1
	s_mov_b32 vcc_hi, s21
	s_lshl_b64 s[10:11], vcc, 7
	s_add_u32 s17, s40, s6
	s_addc_u32 vcc_lo, s41, s7
	s_and_b64 s[6:7], exec, s[62:63]
	s_cselect_b32 vcc_hi, s82, vcc_lo
	s_cselect_b32 vcc_lo, s48, s17
	s_add_i32 s17, 0, 0x10000
	v_add_u32_e32 v133, s17, v147
	s_add_i32 s62, 0, 0x14000
	ds_read_b128 v[140:143], v133
	ds_read_b128 v[150:153], v133 offset:1024
	ds_read_b128 v[154:157], v133 offset:2048
	ds_read_b128 v[158:161], v133 offset:3072
	ds_read_b128 v[186:189], v133 offset:16384
	ds_read_b128 v[190:193], v133 offset:17408
	ds_read_b128 v[194:197], v133 offset:18432
	ds_read_b128 v[198:201], v133 offset:19456
	s_add_u32 s6, s68, s10
	s_addc_u32 s7, s16, s11
	s_add_i32 m0, s54, 0xc000
	ds_read_b128 v[202:205], v184
	ds_read_b128 v[206:209], v184 offset:1024
	ds_read_b128 v[210:213], v184 offset:2048
	ds_read_b128 v[214:217], v184 offset:3072
	ds_read_b128 v[218:221], v184 offset:4096
	ds_read_b128 v[222:225], v184 offset:5120
	ds_read_b128 v[226:229], v184 offset:6144
	ds_read_b128 v[230:233], v184 offset:7168
	global_load_lds_dwordx4 v134, s[6:7]
	s_add_u32 s6, s6, s66
	s_addc_u32 s7, s7, s67
	s_add_i32 m0, s54, 0xe000
	s_nop 0
	global_load_lds_dwordx4 v134, s[6:7]
	s_waitcnt vmcnt(16)
	s_waitcnt lgkmcnt(0)
	s_setprio 1
	s_barrier
	v_mfma_f32_16x16x32_bf16 v[126:129], v[140:143], v[202:205], v[126:129]
	v_mfma_f32_16x16x32_bf16 v[122:125], v[154:157], v[202:205], v[122:125]
	v_mfma_f32_16x16x32_bf16 v[110:113], v[140:143], v[210:213], v[110:113]
	v_mfma_f32_16x16x32_bf16 v[106:109], v[154:157], v[210:213], v[106:109]
	v_mfma_f32_16x16x32_bf16 v[94:97], v[140:143], v[218:221], v[94:97]
	v_mfma_f32_16x16x32_bf16 v[90:93], v[154:157], v[218:221], v[90:93]
	v_mfma_f32_16x16x32_bf16 v[78:81], v[140:143], v[226:229], v[78:81]
	v_mfma_f32_16x16x32_bf16 v[74:77], v[154:157], v[226:229], v[74:77]
	v_mfma_f32_16x16x32_bf16 v[126:129], v[150:153], v[206:209], v[126:129]
	v_mfma_f32_16x16x32_bf16 v[122:125], v[158:161], v[206:209], v[122:125]
	v_mfma_f32_16x16x32_bf16 v[110:113], v[150:153], v[214:217], v[110:113]
	v_mfma_f32_16x16x32_bf16 v[106:109], v[158:161], v[214:217], v[106:109]
	v_mfma_f32_16x16x32_bf16 v[94:97], v[150:153], v[222:225], v[94:97]
	v_mfma_f32_16x16x32_bf16 v[90:93], v[158:161], v[222:225], v[90:93]
	v_mfma_f32_16x16x32_bf16 v[78:81], v[150:153], v[230:233], v[78:81]
	v_mfma_f32_16x16x32_bf16 v[74:77], v[158:161], v[230:233], v[74:77]
	v_mfma_f32_16x16x32_bf16 v[118:121], v[186:189], v[202:205], v[118:121]
	v_mfma_f32_16x16x32_bf16 v[114:117], v[194:197], v[202:205], v[114:117]
	v_mfma_f32_16x16x32_bf16 v[102:105], v[186:189], v[210:213], v[102:105]
	v_mfma_f32_16x16x32_bf16 v[98:101], v[194:197], v[210:213], v[98:101]
	v_mfma_f32_16x16x32_bf16 v[86:89], v[186:189], v[218:221], v[86:89]
	v_mfma_f32_16x16x32_bf16 v[82:85], v[194:197], v[218:221], v[82:85]
	v_mfma_f32_16x16x32_bf16 v[70:73], v[186:189], v[226:229], v[70:73]
	v_mfma_f32_16x16x32_bf16 v[66:69], v[194:197], v[226:229], v[66:69]
	v_mfma_f32_16x16x32_bf16 v[118:121], v[190:193], v[206:209], v[118:121]
	v_mfma_f32_16x16x32_bf16 v[114:117], v[198:201], v[206:209], v[114:117]
	v_mfma_f32_16x16x32_bf16 v[102:105], v[190:193], v[214:217], v[102:105]
	v_mfma_f32_16x16x32_bf16 v[98:101], v[198:201], v[214:217], v[98:101]
	v_mfma_f32_16x16x32_bf16 v[86:89], v[190:193], v[222:225], v[86:89]
	v_mfma_f32_16x16x32_bf16 v[82:85], v[198:201], v[222:225], v[82:85]
	v_mfma_f32_16x16x32_bf16 v[70:73], v[190:193], v[230:233], v[70:73]
	v_mfma_f32_16x16x32_bf16 v[66:69], v[198:201], v[230:233], v[66:69]
	s_barrier
	s_setprio 0
	s_add_i32 s10, s17, s47
	s_ashr_i32 s11, s73, 31
	s_mov_b32 m0, s10
	s_add_u32 s6, s28, s73
	ds_read_b128 v[202:205], v184 offset:16384
	ds_read_b128 v[206:209], v184 offset:17408
	ds_read_b128 v[210:213], v184 offset:18432
	ds_read_b128 v[214:217], v184 offset:19456
	ds_read_b128 v[218:221], v184 offset:20480
	ds_read_b128 v[222:225], v184 offset:21504
	ds_read_b128 v[226:229], v184 offset:22528
	ds_read_b128 v[230:233], v184 offset:23552
	global_load_lds_dwordx4 v0, s[28:29]
	s_addc_u32 s7, s29, s11
	s_add_i32 m0, s10, 0x2000
	s_nop 0
	global_load_lds_dwordx4 v0, s[6:7]
	s_ashr_i32 s7, s19, 31
	s_add_u32 s6, s28, s19
	s_addc_u32 s7, s29, s7
	s_add_i32 s10, s62, s47
	s_mov_b32 m0, s10
	s_nop 0
	global_load_lds_dwordx4 v0, s[6:7]
	s_add_u32 s6, s6, s73
	s_addc_u32 s7, s7, s11
	s_add_i32 m0, s10, 0x2000
	s_nop 0
	global_load_lds_dwordx4 v0, s[6:7]
	s_add_u32 s6, vcc_lo, s64
	s_mov_b32 m0, s54
	s_addc_u32 s7, vcc_hi, s65
	global_load_lds_dwordx4 v136, vcc
	s_mov_b32 m0, s55
	s_nop 0
	global_load_lds_dwordx4 v136, s[6:7]
	s_waitcnt vmcnt(16)
	s_waitcnt lgkmcnt(0)
	s_setprio 1
	s_barrier
; #define PG8_STAGE(bufoff, gbase, off, q) do { \
;         __builtin_amdgcn_global_load_lds((const unsigned*)((const char*)(gbase) + (off)), (LAS unsigned*)(lds + (bufoff) + ldsw), 16, 0, 0); \
;         __builtin_amdgcn_global_load_lds((const unsigned*)((const char*)(gbase) + (q) + (off)), (LAS unsigned*)(lds + (bufoff) + ldsw + 8192), 16, 0, 0); } while (0)
; #define PG8_LDA(dst, b, h) do { _Pragma("unroll") for (int m = 0; m < 4; ++m) _Pragma("unroll") for (int k = 0; k < 2; ++k) dst[m][k] = *(const LAS bf16x8*)(lds + PG8_SA(b, h) + aoff + m * 2048 + k * 1024); } while (0)
; #define PG8_LDB(dst, b, h) do { _Pragma("unroll") for (int n = 0; n < 2; ++n) _Pragma("unroll") for (int k = 0; k < 2; ++k) dst[n][k] = *(const LAS bf16x8*)(lds + PG8_SB(b, h) + boff + n * 2048 + k * 1024); } while (0)
; #define PG8_MMA(ai, bj, At, Bt) do { __builtin_amdgcn_s_setprio(1); _Pragma("unroll") for (int m = 0; m < 4; ++m) _Pragma("unroll") for (int n = 0; n < 2; ++n) _Pragma("unroll") for (int k = 0; k < 2; ++k) \
;         acc[ai][bj][m][n] = __builtin_amdgcn_mfma_f32_16x16x32_bf16(Bt[n][k], At[m][k], acc[ai][bj][m][n], 0, 0, 0); __builtin_amdgcn_s_setprio(0); } while (0)
; #define PG8_WAIT_V(n) asm volatile("s_waitcnt vmcnt(" #n ")" ::: "memory")
; #define PG8_WAIT_L(n) asm volatile("s_waitcnt lgkmcnt(" #n ")" ::: "memory")
; #define PG8_BAR __builtin_amdgcn_s_barrier()
; #define PG8_SCHED __builtin_amdgcn_sched_barrier(0)
; template <class Epi, class Sched>
; __device__ __forceinline__ void gemm_phase(LAS unsigned char* lds, const int tid, const Sched& S, const Epi& E) {
;     ...
;             PG8_WAIT_V(8); PG8_WAIT_L(0); PG8_BAR; PG8_MMA(1, 0, At, B0); PG8_MMA(1, 1, At, B1); PG8_BAR; PG8_SCHED;
;             PG8_LDB(B0, 1, 0); PG8_LDB(B1, 1, 1); PG8_SCHED; PG8_LDA(At, 1, 0); PG8_STAGE(PG8_SA(0, 1), a2 + hA2, oA2, qA2);
;             PG8_WAIT_V(8); PG8_WAIT_L(0); PG8_BAR; PG8_MMA(0, 0, At, B0); PG8_MMA(0, 1, At, B1); PG8_BAR; PG8_SCHED;
	v_mfma_f32_16x16x32_bf16 v[62:65], v[140:143], v[202:205], v[62:65]
	v_mfma_f32_16x16x32_bf16 v[58:61], v[154:157], v[202:205], v[58:61]
	v_mfma_f32_16x16x32_bf16 v[46:49], v[140:143], v[210:213], v[46:49]
	v_mfma_f32_16x16x32_bf16 v[42:45], v[154:157], v[210:213], v[42:45]
	v_mfma_f32_16x16x32_bf16 v[30:33], v[140:143], v[218:221], v[30:33]
	v_mfma_f32_16x16x32_bf16 v[26:29], v[154:157], v[218:221], v[26:29]
	v_mfma_f32_16x16x32_bf16 v[14:17], v[140:143], v[226:229], v[14:17]
	v_mfma_f32_16x16x32_bf16 v[10:13], v[154:157], v[226:229], v[10:13]
	v_mfma_f32_16x16x32_bf16 v[62:65], v[150:153], v[206:209], v[62:65]
	v_mfma_f32_16x16x32_bf16 v[58:61], v[158:161], v[206:209], v[58:61]
	v_mfma_f32_16x16x32_bf16 v[46:49], v[150:153], v[214:217], v[46:49]
	v_mfma_f32_16x16x32_bf16 v[42:45], v[158:161], v[214:217], v[42:45]
	v_mfma_f32_16x16x32_bf16 v[30:33], v[150:153], v[222:225], v[30:33]
	v_mfma_f32_16x16x32_bf16 v[26:29], v[158:161], v[222:225], v[26:29]
	v_mfma_f32_16x16x32_bf16 v[14:17], v[150:153], v[230:233], v[14:17]
	v_mfma_f32_16x16x32_bf16 v[10:13], v[158:161], v[230:233], v[10:13]
	v_mfma_f32_16x16x32_bf16 v[54:57], v[186:189], v[202:205], v[54:57]
	v_mfma_f32_16x16x32_bf16 v[50:53], v[194:197], v[202:205], v[50:53]
	v_mfma_f32_16x16x32_bf16 v[38:41], v[186:189], v[210:213], v[38:41]
	v_mfma_f32_16x16x32_bf16 v[34:37], v[194:197], v[210:213], v[34:37]
	v_mfma_f32_16x16x32_bf16 v[22:25], v[186:189], v[218:221], v[22:25]
	v_mfma_f32_16x16x32_bf16 v[18:21], v[194:197], v[218:221], v[18:21]
	v_mfma_f32_16x16x32_bf16 v[6:9], v[186:189], v[226:229], v[6:9]
	v_mfma_f32_16x16x32_bf16 v[2:5], v[194:197], v[226:229], v[2:5]
	v_mfma_f32_16x16x32_bf16 v[54:57], v[190:193], v[206:209], v[54:57]
	v_mfma_f32_16x16x32_bf16 v[50:53], v[198:201], v[206:209], v[50:53]
	v_mfma_f32_16x16x32_bf16 v[38:41], v[190:193], v[214:217], v[38:41]
	v_mfma_f32_16x16x32_bf16 v[34:37], v[198:201], v[214:217], v[34:37]
	v_mfma_f32_16x16x32_bf16 v[22:25], v[190:193], v[222:225], v[22:25]
	v_mfma_f32_16x16x32_bf16 v[18:21], v[198:201], v[222:225], v[18:21]
	v_mfma_f32_16x16x32_bf16 v[6:9], v[190:193], v[230:233], v[6:9]
	v_mfma_f32_16x16x32_bf16 v[2:5], v[198:201], v[230:233], v[2:5]
	s_barrier
	s_setprio 0
	s_add_i32 s10, 0, 0x18000
	s_add_i32 s11, 0, 0x1c000
	ds_read_b128 v[140:143], v133 offset:32768
	ds_read_b128 v[150:153], v133 offset:33792
	ds_read_b128 v[154:157], v133 offset:34816
	ds_read_b128 v[158:161], v133 offset:35840
	ds_read_b128 v[186:189], v133 offset:49152
	ds_read_b128 v[190:193], v133 offset:50176
	ds_read_b128 v[194:197], v133 offset:51200
	ds_read_b128 v[198:201], v133 offset:52224
	s_add_u32 s6, vcc_lo, s58
	s_addc_u32 s7, vcc_hi, s59
	s_mov_b32 m0, s91
	ds_read_b128 v[202:205], v184 offset:32768
	ds_read_b128 v[206:209], v184 offset:33792
	ds_read_b128 v[210:213], v184 offset:34816
	ds_read_b128 v[214:217], v184 offset:35840
	ds_read_b128 v[218:221], v184 offset:36864
	ds_read_b128 v[222:225], v184 offset:37888
	ds_read_b128 v[226:229], v184 offset:38912
	ds_read_b128 v[230:233], v184 offset:39936
	global_load_lds_dwordx4 v136, s[6:7]
	s_add_u32 s6, s6, s64
	s_addc_u32 s7, s7, s65
	s_mov_b32 m0, s93
	s_nop 0
	global_load_lds_dwordx4 v136, s[6:7]
	s_waitcnt vmcnt(8)
	s_waitcnt lgkmcnt(0)
	s_setprio 1
	s_barrier
	v_mfma_f32_16x16x32_bf16 v[126:129], v[140:143], v[202:205], v[126:129]
	v_mfma_f32_16x16x32_bf16 v[122:125], v[154:157], v[202:205], v[122:125]
	v_mfma_f32_16x16x32_bf16 v[110:113], v[140:143], v[210:213], v[110:113]
	v_mfma_f32_16x16x32_bf16 v[106:109], v[154:157], v[210:213], v[106:109]
	v_mfma_f32_16x16x32_bf16 v[94:97], v[140:143], v[218:221], v[94:97]
	v_mfma_f32_16x16x32_bf16 v[90:93], v[154:157], v[218:221], v[90:93]
	v_mfma_f32_16x16x32_bf16 v[78:81], v[140:143], v[226:229], v[78:81]
	v_mfma_f32_16x16x32_bf16 v[74:77], v[154:157], v[226:229], v[74:77]
	v_mfma_f32_16x16x32_bf16 v[126:129], v[150:153], v[206:209], v[126:129]
	v_mfma_f32_16x16x32_bf16 v[122:125], v[158:161], v[206:209], v[122:125]
	v_mfma_f32_16x16x32_bf16 v[110:113], v[150:153], v[214:217], v[110:113]
	v_mfma_f32_16x16x32_bf16 v[106:109], v[158:161], v[214:217], v[106:109]
	v_mfma_f32_16x16x32_bf16 v[94:97], v[150:153], v[222:225], v[94:97]
	v_mfma_f32_16x16x32_bf16 v[90:93], v[158:161], v[222:225], v[90:93]
	v_mfma_f32_16x16x32_bf16 v[78:81], v[150:153], v[230:233], v[78:81]
	v_mfma_f32_16x16x32_bf16 v[74:77], v[158:161], v[230:233], v[74:77]
	v_mfma_f32_16x16x32_bf16 v[118:121], v[186:189], v[202:205], v[118:121]
	v_mfma_f32_16x16x32_bf16 v[114:117], v[194:197], v[202:205], v[114:117]
	v_mfma_f32_16x16x32_bf16 v[102:105], v[186:189], v[210:213], v[102:105]
	v_mfma_f32_16x16x32_bf16 v[98:101], v[194:197], v[210:213], v[98:101]
	v_mfma_f32_16x16x32_bf16 v[86:89], v[186:189], v[218:221], v[86:89]
	v_mfma_f32_16x16x32_bf16 v[82:85], v[194:197], v[218:221], v[82:85]
	v_mfma_f32_16x16x32_bf16 v[70:73], v[186:189], v[226:229], v[70:73]
	v_mfma_f32_16x16x32_bf16 v[66:69], v[194:197], v[226:229], v[66:69]
	v_mfma_f32_16x16x32_bf16 v[118:121], v[190:193], v[206:209], v[118:121]
	v_mfma_f32_16x16x32_bf16 v[114:117], v[198:201], v[206:209], v[114:117]
	v_mfma_f32_16x16x32_bf16 v[102:105], v[190:193], v[214:217], v[102:105]
	v_mfma_f32_16x16x32_bf16 v[98:101], v[198:201], v[214:217], v[98:101]
	v_mfma_f32_16x16x32_bf16 v[86:89], v[190:193], v[222:225], v[86:89]
	v_mfma_f32_16x16x32_bf16 v[82:85], v[198:201], v[222:225], v[82:85]
	v_mfma_f32_16x16x32_bf16 v[70:73], v[190:193], v[230:233], v[70:73]
	v_mfma_f32_16x16x32_bf16 v[66:69], v[198:201], v[230:233], v[66:69]
	s_barrier
; #define PG8_STAGE(bufoff, gbase, off, q) do { \
;         __builtin_amdgcn_global_load_lds((const unsigned*)((const char*)(gbase) + (off)), (LAS unsigned*)(lds + (bufoff) + ldsw), 16, 0, 0); \
;         __builtin_amdgcn_global_load_lds((const unsigned*)((const char*)(gbase) + (q) + (off)), (LAS unsigned*)(lds + (bufoff) + ldsw + 8192), 16, 0, 0); } while (0)
; #define PG8_LDA(dst, b, h) do { _Pragma("unroll") for (int m = 0; m < 4; ++m) _Pragma("unroll") for (int k = 0; k < 2; ++k) dst[m][k] = *(const LAS bf16x8*)(lds + PG8_SA(b, h) + aoff + m * 2048 + k * 1024); } while (0)
; #define PG8_MMA(ai, bj, At, Bt) do { __builtin_amdgcn_s_setprio(1); _Pragma("unroll") for (int m = 0; m < 4; ++m) _Pragma("unroll") for (int n = 0; n < 2; ++n) _Pragma("unroll") for (int k = 0; k < 2; ++k) \
;         acc[ai][bj][m][n] = __builtin_amdgcn_mfma_f32_16x16x32_bf16(Bt[n][k], At[m][k], acc[ai][bj][m][n], 0, 0, 0); __builtin_amdgcn_s_setprio(0); } while (0)
; #define PG8_WAIT_V(n) asm volatile("s_waitcnt vmcnt(" #n ")" ::: "memory")
; #define PG8_WAIT_L(n) asm volatile("s_waitcnt lgkmcnt(" #n ")" ::: "memory")
; #define PG8_BAR __builtin_amdgcn_s_barrier()
; #define PG8_SCHED __builtin_amdgcn_sched_barrier(0)
; template <class Epi, class Sched>
; __device__ __forceinline__ void gemm_phase(LAS unsigned char* lds, const int tid, const Sched& S, const Epi& E) {
;     ...
;             PG8_LDA(At, 1, 1); PG8_STAGE(PG8_SB(1, 0), b3, oB2, qB2); PG8_STAGE(PG8_SB(1, 1), b3 + hB2, oB2, qB2); PG8_STAGE(PG8_SA(1, 0), a3, oA2, qA2);
;             PG8_WAIT_V(8); PG8_WAIT_L(0); PG8_BAR; PG8_MMA(1, 0, At, B0); PG8_MMA(1, 1, At, B1); PG8_BAR; PG8_SCHED;
;         }
	s_setprio 0
	s_add_i32 s6, s10, s47
	s_add_i32 m0, s6, 0xffffff80
	ds_read_b128 v[202:205], v184 offset:49152
	ds_read_b128 v[206:209], v184 offset:50176
	ds_read_b128 v[210:213], v184 offset:51200
	ds_read_b128 v[214:217], v184 offset:52224
	ds_read_b128 v[218:221], v184 offset:53248
	ds_read_b128 v[222:225], v184 offset:54272
	ds_read_b128 v[226:229], v184 offset:55296
	ds_read_b128 v[230:233], v184 offset:56320
	global_load_lds_dwordx4 v0, s[28:29] offset:128
	s_add_i32 m0, s6, 0x1f80
	s_add_i32 s6, s11, s47
	s_ashr_i32 s100, s73, 31
	s_add_u32 s98, s28, s73
	s_addc_u32 s99, s29, s100
	global_load_lds_dwordx4 v0, s[98:99] offset:128
	s_add_i32 m0, s6, 0xffffff80
	s_nop 0
	s_ashr_i32 s101, s19, 31
	s_add_u32 s98, s28, s19
	s_addc_u32 s99, s29, s101
	global_load_lds_dwordx4 v0, s[98:99] offset:128
	s_add_i32 m0, s6, 0x1f80
	s_nop 0
	s_add_u32 s98, s98, s73
	s_addc_u32 s99, s99, s100
	global_load_lds_dwordx4 v0, s[98:99] offset:128
	s_add_i32 m0, s77, 0xffffff80
	s_nop 0
	global_load_lds_dwordx4 v136, vcc offset:128
	s_add_i32 m0, s88, 0xffffff80
	s_nop 0
	s_add_u32 s98, vcc_lo, s64
	s_addc_u32 s99, vcc_hi, s65
	global_load_lds_dwordx4 v136, s[98:99] offset:128
	s_waitcnt vmcnt(8)
	s_waitcnt lgkmcnt(0)
	s_setprio 1
	s_barrier
	v_mfma_f32_16x16x32_bf16 v[62:65], v[140:143], v[202:205], v[62:65]
	v_mfma_f32_16x16x32_bf16 v[58:61], v[154:157], v[202:205], v[58:61]
	v_mfma_f32_16x16x32_bf16 v[46:49], v[140:143], v[210:213], v[46:49]
	v_mfma_f32_16x16x32_bf16 v[42:45], v[154:157], v[210:213], v[42:45]
	v_mfma_f32_16x16x32_bf16 v[30:33], v[140:143], v[218:221], v[30:33]
	v_mfma_f32_16x16x32_bf16 v[26:29], v[154:157], v[218:221], v[26:29]
	v_mfma_f32_16x16x32_bf16 v[14:17], v[140:143], v[226:229], v[14:17]
	v_mfma_f32_16x16x32_bf16 v[10:13], v[154:157], v[226:229], v[10:13]
	v_mfma_f32_16x16x32_bf16 v[62:65], v[150:153], v[206:209], v[62:65]
	v_mfma_f32_16x16x32_bf16 v[58:61], v[158:161], v[206:209], v[58:61]
	v_mfma_f32_16x16x32_bf16 v[46:49], v[150:153], v[214:217], v[46:49]
	v_mfma_f32_16x16x32_bf16 v[42:45], v[158:161], v[214:217], v[42:45]
	v_mfma_f32_16x16x32_bf16 v[30:33], v[150:153], v[222:225], v[30:33]
	v_mfma_f32_16x16x32_bf16 v[26:29], v[158:161], v[222:225], v[26:29]
	v_mfma_f32_16x16x32_bf16 v[14:17], v[150:153], v[230:233], v[14:17]
	v_mfma_f32_16x16x32_bf16 v[10:13], v[158:161], v[230:233], v[10:13]
	v_mfma_f32_16x16x32_bf16 v[54:57], v[186:189], v[202:205], v[54:57]
	v_mfma_f32_16x16x32_bf16 v[50:53], v[194:197], v[202:205], v[50:53]
	v_mfma_f32_16x16x32_bf16 v[38:41], v[186:189], v[210:213], v[38:41]
	v_mfma_f32_16x16x32_bf16 v[34:37], v[194:197], v[210:213], v[34:37]
	v_mfma_f32_16x16x32_bf16 v[22:25], v[186:189], v[218:221], v[22:25]
	v_mfma_f32_16x16x32_bf16 v[18:21], v[194:197], v[218:221], v[18:21]
	v_mfma_f32_16x16x32_bf16 v[6:9], v[186:189], v[226:229], v[6:9]
	v_mfma_f32_16x16x32_bf16 v[2:5], v[194:197], v[226:229], v[2:5]
	v_mfma_f32_16x16x32_bf16 v[54:57], v[190:193], v[206:209], v[54:57]
	v_mfma_f32_16x16x32_bf16 v[50:53], v[198:201], v[206:209], v[50:53]
	v_mfma_f32_16x16x32_bf16 v[38:41], v[190:193], v[214:217], v[38:41]
	v_mfma_f32_16x16x32_bf16 v[34:37], v[198:201], v[214:217], v[34:37]
	v_mfma_f32_16x16x32_bf16 v[22:25], v[190:193], v[222:225], v[22:25]
	v_mfma_f32_16x16x32_bf16 v[18:21], v[198:201], v[222:225], v[18:21]
	v_mfma_f32_16x16x32_bf16 v[6:9], v[190:193], v[230:233], v[6:9]
	v_mfma_f32_16x16x32_bf16 v[2:5], v[198:201], v[230:233], v[2:5]
	s_barrier
	s_setprio 0
	s_cmp_ge_i32 s20, s37
	s_cbranch_scc1 .LBB0_177
	s_mov_b32 s17, s20
	s_branch .LBB0_173

; #define PG8_STAGE(bufoff, gbase, off, q) do { \
;         __builtin_amdgcn_global_load_lds((const unsigned*)((const char*)(gbase) + (off)), (LAS unsigned*)(lds + (bufoff) + ldsw), 16, 0, 0); \
;         __builtin_amdgcn_global_load_lds((const unsigned*)((const char*)(gbase) + (q) + (off)), (LAS unsigned*)(lds + (bufoff) + ldsw + 8192), 16, 0, 0); } while (0)
; #define PG8_LDA(dst, b, h) do { _Pragma("unroll") for (int m = 0; m < 4; ++m) _Pragma("unroll") for (int k = 0; k < 2; ++k) dst[m][k] = *(const LAS bf16x8*)(lds + PG8_SA(b, h) + aoff + m * 2048 + k * 1024); } while (0)
; #define PG8_LDB(dst, b, h) do { _Pragma("unroll") for (int n = 0; n < 2; ++n) _Pragma("unroll") for (int k = 0; k < 2; ++k) dst[n][k] = *(const LAS bf16x8*)(lds + PG8_SB(b, h) + boff + n * 2048 + k * 1024); } while (0)
; #define PG8_MMA(ai, bj, At, Bt) do { __builtin_amdgcn_s_setprio(1); _Pragma("unroll") for (int m = 0; m < 4; ++m) _Pragma("unroll") for (int n = 0; n < 2; ++n) _Pragma("unroll") for (int k = 0; k < 2; ++k) \
;         acc[ai][bj][m][n] = __builtin_amdgcn_mfma_f32_16x16x32_bf16(Bt[n][k], At[m][k], acc[ai][bj][m][n], 0, 0, 0); __builtin_amdgcn_s_setprio(0); } while (0)
; template <class Epi, class Sched>
; __device__ __forceinline__ void gemm_phase(LAS unsigned char* lds, const int tid, const Sched& S, const Epi& E) {
;     ...
;             const bool last = (t == nt - 2);
;             const char* a1 = cA + (size_t)(t + 1) * kstep;
;             const char* a2 = last ? nA : cA + (size_t)(t + 2) * kstep; const char* b2 = last ? nB : cB + (size_t)(t + 2) * kstep;
;             const char* a3 = a2 + kstep; const char* b3 = b2 + kstep;
;             const unsigned oA2 = last ? noffA : offA, oB2 = last ? noffB : offB;
;             const int qA2 = last ? nqA : qA, qB2 = last ? nqB : qB, hA2 = last ? nhA : hA, hB2 = last ? nhB : hB;
;             PG8_LDB(B0, 0, 0); PG8_LDB(B1, 0, 1); PG8_SCHED; PG8_LDA(At, 0, 0); PG8_STAGE(PG8_SA(1, 1), a1 + hA, offA, qA);
;             PG8_WAIT_V(8); PG8_WAIT_L(0); PG8_BAR; PG8_MMA(0, 0, At, B0); PG8_MMA(0, 1, At, B1); PG8_BAR; PG8_SCHED;
;             PG8_LDA(At, 0, 1); PG8_STAGE(PG8_SB(0, 0), b2, oB2, qB2); PG8_STAGE(PG8_SB(0, 1), b2 + hB2, oB2, qB2); PG8_STAGE(PG8_SA(0, 0), a2, oA2, qA2);
;             PG8_WAIT_V(8); PG8_WAIT_L(0); PG8_BAR; PG8_MMA(1, 0, At, B0); PG8_MMA(1, 1, At, B1); PG8_BAR; PG8_SCHED;
.Lk0b_175:
	s_or_b32 vcc_lo, s17, 1
	s_mov_b32 vcc_hi, s21
	s_lshl_b64 s[10:11], vcc, 7
	s_add_u32 s17, s40, s6
	s_addc_u32 vcc_lo, s41, s7
	s_and_b64 s[6:7], exec, s[62:63]
	s_cselect_b32 vcc_hi, s82, vcc_lo
	s_cselect_b32 vcc_lo, s48, s17
	s_add_i32 s17, 0, 0x10000
	v_add_u32_e32 v133, s17, v147
	s_add_i32 s62, 0, 0x14000
	ds_read_b128 v[140:143], v133
	ds_read_b128 v[150:153], v133 offset:1024
	ds_read_b128 v[154:157], v133 offset:2048
	ds_read_b128 v[158:161], v133 offset:3072
	ds_read_b128 v[186:189], v133 offset:16384
	ds_read_b128 v[190:193], v133 offset:17408
	ds_read_b128 v[194:197], v133 offset:18432
	ds_read_b128 v[198:201], v133 offset:19456
	s_add_u32 s6, s68, s10
	s_addc_u32 s7, s16, s11
	s_add_i32 m0, s54, 0xc000
	ds_read_b128 v[202:205], v184
	ds_read_b128 v[206:209], v184 offset:1024
	ds_read_b128 v[210:213], v184 offset:2048
	ds_read_b128 v[214:217], v184 offset:3072
	ds_read_b128 v[218:221], v184 offset:4096
	ds_read_b128 v[222:225], v184 offset:5120
	ds_read_b128 v[226:229], v184 offset:6144
	ds_read_b128 v[230:233], v184 offset:7168
	global_load_lds_dwordx4 v134, s[6:7]
	s_add_u32 s6, s6, s66
	s_addc_u32 s7, s7, s67
	s_add_i32 m0, s54, 0xe000
	s_nop 0
	global_load_lds_dwordx4 v134, s[6:7]
	s_waitcnt vmcnt(24)
	s_waitcnt lgkmcnt(0)
	s_setprio 1
	s_barrier
	v_mfma_f32_16x16x32_bf16 v[126:129], v[140:143], v[202:205], v[126:129]
	v_mfma_f32_16x16x32_bf16 v[122:125], v[154:157], v[202:205], v[122:125]
	v_mfma_f32_16x16x32_bf16 v[110:113], v[140:143], v[210:213], v[110:113]
	v_mfma_f32_16x16x32_bf16 v[106:109], v[154:157], v[210:213], v[106:109]
	v_mfma_f32_16x16x32_bf16 v[94:97], v[140:143], v[218:221], v[94:97]
	v_mfma_f32_16x16x32_bf16 v[90:93], v[154:157], v[218:221], v[90:93]
	v_mfma_f32_16x16x32_bf16 v[78:81], v[140:143], v[226:229], v[78:81]
	v_mfma_f32_16x16x32_bf16 v[74:77], v[154:157], v[226:229], v[74:77]
	v_mfma_f32_16x16x32_bf16 v[126:129], v[150:153], v[206:209], v[126:129]
	v_mfma_f32_16x16x32_bf16 v[122:125], v[158:161], v[206:209], v[122:125]
	v_mfma_f32_16x16x32_bf16 v[110:113], v[150:153], v[214:217], v[110:113]
	v_mfma_f32_16x16x32_bf16 v[106:109], v[158:161], v[214:217], v[106:109]
	v_mfma_f32_16x16x32_bf16 v[94:97], v[150:153], v[222:225], v[94:97]
	v_mfma_f32_16x16x32_bf16 v[90:93], v[158:161], v[222:225], v[90:93]
	v_mfma_f32_16x16x32_bf16 v[78:81], v[150:153], v[230:233], v[78:81]
	v_mfma_f32_16x16x32_bf16 v[74:77], v[158:161], v[230:233], v[74:77]
	v_mfma_f32_16x16x32_bf16 v[118:121], v[186:189], v[202:205], v[118:121]
	v_mfma_f32_16x16x32_bf16 v[114:117], v[194:197], v[202:205], v[114:117]
	v_mfma_f32_16x16x32_bf16 v[102:105], v[186:189], v[210:213], v[102:105]
	v_mfma_f32_16x16x32_bf16 v[98:101], v[194:197], v[210:213], v[98:101]
	v_mfma_f32_16x16x32_bf16 v[86:89], v[186:189], v[218:221], v[86:89]
	v_mfma_f32_16x16x32_bf16 v[82:85], v[194:197], v[218:221], v[82:85]
	v_mfma_f32_16x16x32_bf16 v[70:73], v[186:189], v[226:229], v[70:73]
	v_mfma_f32_16x16x32_bf16 v[66:69], v[194:197], v[226:229], v[66:69]
	v_mfma_f32_16x16x32_bf16 v[118:121], v[190:193], v[206:209], v[118:121]
	v_mfma_f32_16x16x32_bf16 v[114:117], v[198:201], v[206:209], v[114:117]
	v_mfma_f32_16x16x32_bf16 v[102:105], v[190:193], v[214:217], v[102:105]
	v_mfma_f32_16x16x32_bf16 v[98:101], v[198:201], v[214:217], v[98:101]
	v_mfma_f32_16x16x32_bf16 v[86:89], v[190:193], v[222:225], v[86:89]
	v_mfma_f32_16x16x32_bf16 v[82:85], v[198:201], v[222:225], v[82:85]
	v_mfma_f32_16x16x32_bf16 v[70:73], v[190:193], v[230:233], v[70:73]
	v_mfma_f32_16x16x32_bf16 v[66:69], v[198:201], v[230:233], v[66:69]
	s_barrier
	s_setprio 0
	s_add_i32 s10, s17, s47
	s_ashr_i32 s11, s73, 31
	s_mov_b32 m0, s10
	s_add_u32 s6, s28, s73
	ds_read_b128 v[202:205], v184 offset:16384
	ds_read_b128 v[206:209], v184 offset:17408
	ds_read_b128 v[210:213], v184 offset:18432
	ds_read_b128 v[214:217], v184 offset:19456
	ds_read_b128 v[218:221], v184 offset:20480
	ds_read_b128 v[222:225], v184 offset:21504
	ds_read_b128 v[226:229], v184 offset:22528
	ds_read_b128 v[230:233], v184 offset:23552
	global_load_lds_dwordx4 v0, s[28:29]
	s_addc_u32 s7, s29, s11
	s_add_i32 m0, s10, 0x2000
	s_nop 0
	global_load_lds_dwordx4 v0, s[6:7]
	s_ashr_i32 s7, s19, 31
	s_add_u32 s6, s28, s19
	s_addc_u32 s7, s29, s7
	s_add_i32 s10, s62, s47
	s_mov_b32 m0, s10
	s_nop 0
	global_load_lds_dwordx4 v0, s[6:7]
	s_add_u32 s6, s6, s73
	s_addc_u32 s7, s7, s11
	s_add_i32 m0, s10, 0x2000
	s_nop 0
	global_load_lds_dwordx4 v0, s[6:7]
	s_add_u32 s6, vcc_lo, s64
	s_mov_b32 m0, s54
	s_addc_u32 s7, vcc_hi, s65
	global_load_lds_dwordx4 v136, vcc
	s_mov_b32 m0, s55
	s_nop 0
	global_load_lds_dwordx4 v136, s[6:7]
	s_waitcnt vmcnt(24)
	s_waitcnt lgkmcnt(0)
	s_setprio 1
	s_barrier
; #define PG8_STAGE(bufoff, gbase, off, q) do { \
;         __builtin_amdgcn_global_load_lds((const unsigned*)((const char*)(gbase) + (off)), (LAS unsigned*)(lds + (bufoff) + ldsw), 16, 0, 0); \
;         __builtin_amdgcn_global_load_lds((const unsigned*)((const char*)(gbase) + (q) + (off)), (LAS unsigned*)(lds + (bufoff) + ldsw + 8192), 16, 0, 0); } while (0)
; #define PG8_LDA(dst, b, h) do { _Pragma("unroll") for (int m = 0; m < 4; ++m) _Pragma("unroll") for (int k = 0; k < 2; ++k) dst[m][k] = *(const LAS bf16x8*)(lds + PG8_SA(b, h) + aoff + m * 2048 + k * 1024); } while (0)
; #define PG8_LDB(dst, b, h) do { _Pragma("unroll") for (int n = 0; n < 2; ++n) _Pragma("unroll") for (int k = 0; k < 2; ++k) dst[n][k] = *(const LAS bf16x8*)(lds + PG8_SB(b, h) + boff + n * 2048 + k * 1024); } while (0)
; #define PG8_MMA(ai, bj, At, Bt) do { __builtin_amdgcn_s_setprio(1); _Pragma("unroll") for (int m = 0; m < 4; ++m) _Pragma("unroll") for (int n = 0; n < 2; ++n) _Pragma("unroll") for (int k = 0; k < 2; ++k) \
;         acc[ai][bj][m][n] = __builtin_amdgcn_mfma_f32_16x16x32_bf16(Bt[n][k], At[m][k], acc[ai][bj][m][n], 0, 0, 0); __builtin_amdgcn_s_setprio(0); } while (0)
; #define PG8_WAIT_V(n) asm volatile("s_waitcnt vmcnt(" #n ")" ::: "memory")
; #define PG8_WAIT_L(n) asm volatile("s_waitcnt lgkmcnt(" #n ")" ::: "memory")
; #define PG8_BAR __builtin_amdgcn_s_barrier()
; #define PG8_SCHED __builtin_amdgcn_sched_barrier(0)
; template <class Epi, class Sched>
; __device__ __forceinline__ void gemm_phase(LAS unsigned char* lds, const int tid, const Sched& S, const Epi& E) {
;     ...
;             PG8_WAIT_V(8); PG8_WAIT_L(0); PG8_BAR; PG8_MMA(1, 0, At, B0); PG8_MMA(1, 1, At, B1); PG8_BAR; PG8_SCHED;
;             PG8_LDB(B0, 1, 0); PG8_LDB(B1, 1, 1); PG8_SCHED; PG8_LDA(At, 1, 0); PG8_STAGE(PG8_SA(0, 1), a2 + hA2, oA2, qA2);
;             PG8_WAIT_V(8); PG8_WAIT_L(0); PG8_BAR; PG8_MMA(0, 0, At, B0); PG8_MMA(0, 1, At, B1); PG8_BAR; PG8_SCHED;
	v_mfma_f32_16x16x32_bf16 v[62:65], v[140:143], v[202:205], v[62:65]
	v_mfma_f32_16x16x32_bf16 v[58:61], v[154:157], v[202:205], v[58:61]
	v_mfma_f32_16x16x32_bf16 v[46:49], v[140:143], v[210:213], v[46:49]
	v_mfma_f32_16x16x32_bf16 v[42:45], v[154:157], v[210:213], v[42:45]
	v_mfma_f32_16x16x32_bf16 v[30:33], v[140:143], v[218:221], v[30:33]
	v_mfma_f32_16x16x32_bf16 v[26:29], v[154:157], v[218:221], v[26:29]
	v_mfma_f32_16x16x32_bf16 v[14:17], v[140:143], v[226:229], v[14:17]
	v_mfma_f32_16x16x32_bf16 v[10:13], v[154:157], v[226:229], v[10:13]
	v_mfma_f32_16x16x32_bf16 v[62:65], v[150:153], v[206:209], v[62:65]
	v_mfma_f32_16x16x32_bf16 v[58:61], v[158:161], v[206:209], v[58:61]
	v_mfma_f32_16x16x32_bf16 v[46:49], v[150:153], v[214:217], v[46:49]
	v_mfma_f32_16x16x32_bf16 v[42:45], v[158:161], v[214:217], v[42:45]
	v_mfma_f32_16x16x32_bf16 v[30:33], v[150:153], v[222:225], v[30:33]
	v_mfma_f32_16x16x32_bf16 v[26:29], v[158:161], v[222:225], v[26:29]
	v_mfma_f32_16x16x32_bf16 v[14:17], v[150:153], v[230:233], v[14:17]
	v_mfma_f32_16x16x32_bf16 v[10:13], v[158:161], v[230:233], v[10:13]
	v_mfma_f32_16x16x32_bf16 v[54:57], v[186:189], v[202:205], v[54:57]
	v_mfma_f32_16x16x32_bf16 v[50:53], v[194:197], v[202:205], v[50:53]
	v_mfma_f32_16x16x32_bf16 v[38:41], v[186:189], v[210:213], v[38:41]
	v_mfma_f32_16x16x32_bf16 v[34:37], v[194:197], v[210:213], v[34:37]
	v_mfma_f32_16x16x32_bf16 v[22:25], v[186:189], v[218:221], v[22:25]
	v_mfma_f32_16x16x32_bf16 v[18:21], v[194:197], v[218:221], v[18:21]
	v_mfma_f32_16x16x32_bf16 v[6:9], v[186:189], v[226:229], v[6:9]
	v_mfma_f32_16x16x32_bf16 v[2:5], v[194:197], v[226:229], v[2:5]
	v_mfma_f32_16x16x32_bf16 v[54:57], v[190:193], v[206:209], v[54:57]
	v_mfma_f32_16x16x32_bf16 v[50:53], v[198:201], v[206:209], v[50:53]
	v_mfma_f32_16x16x32_bf16 v[38:41], v[190:193], v[214:217], v[38:41]
	v_mfma_f32_16x16x32_bf16 v[34:37], v[198:201], v[214:217], v[34:37]
	v_mfma_f32_16x16x32_bf16 v[22:25], v[190:193], v[222:225], v[22:25]
	v_mfma_f32_16x16x32_bf16 v[18:21], v[198:201], v[222:225], v[18:21]
	v_mfma_f32_16x16x32_bf16 v[6:9], v[190:193], v[230:233], v[6:9]
	v_mfma_f32_16x16x32_bf16 v[2:5], v[198:201], v[230:233], v[2:5]
	s_barrier
	s_setprio 0
	s_add_i32 s10, 0, 0x18000
	s_add_i32 s11, 0, 0x1c000
	ds_read_b128 v[140:143], v133 offset:32768
	ds_read_b128 v[150:153], v133 offset:33792
	ds_read_b128 v[154:157], v133 offset:34816
	ds_read_b128 v[158:161], v133 offset:35840
	ds_read_b128 v[186:189], v133 offset:49152
	ds_read_b128 v[190:193], v133 offset:50176
	ds_read_b128 v[194:197], v133 offset:51200
	ds_read_b128 v[198:201], v133 offset:52224
	s_add_u32 s6, vcc_lo, s58
	s_addc_u32 s7, vcc_hi, s59
	s_mov_b32 m0, s91
	ds_read_b128 v[202:205], v184 offset:32768
	ds_read_b128 v[206:209], v184 offset:33792
	ds_read_b128 v[210:213], v184 offset:34816
	ds_read_b128 v[214:217], v184 offset:35840
	ds_read_b128 v[218:221], v184 offset:36864
	ds_read_b128 v[222:225], v184 offset:37888
	ds_read_b128 v[226:229], v184 offset:38912
	ds_read_b128 v[230:233], v184 offset:39936
	global_load_lds_dwordx4 v136, s[6:7]
	s_add_u32 s6, s6, s64
	s_addc_u32 s7, s7, s65
	s_mov_b32 m0, s93
	s_nop 0
	global_load_lds_dwordx4 v136, s[6:7]
	s_waitcnt vmcnt(8)
	s_waitcnt lgkmcnt(0)
	s_setprio 1
	s_barrier
	v_mfma_f32_16x16x32_bf16 v[126:129], v[140:143], v[202:205], v[126:129]
	v_mfma_f32_16x16x32_bf16 v[122:125], v[154:157], v[202:205], v[122:125]
	v_mfma_f32_16x16x32_bf16 v[110:113], v[140:143], v[210:213], v[110:113]
	v_mfma_f32_16x16x32_bf16 v[106:109], v[154:157], v[210:213], v[106:109]
	v_mfma_f32_16x16x32_bf16 v[94:97], v[140:143], v[218:221], v[94:97]
	v_mfma_f32_16x16x32_bf16 v[90:93], v[154:157], v[218:221], v[90:93]
	v_mfma_f32_16x16x32_bf16 v[78:81], v[140:143], v[226:229], v[78:81]
	v_mfma_f32_16x16x32_bf16 v[74:77], v[154:157], v[226:229], v[74:77]
	v_mfma_f32_16x16x32_bf16 v[126:129], v[150:153], v[206:209], v[126:129]
	v_mfma_f32_16x16x32_bf16 v[122:125], v[158:161], v[206:209], v[122:125]
	v_mfma_f32_16x16x32_bf16 v[110:113], v[150:153], v[214:217], v[110:113]
	v_mfma_f32_16x16x32_bf16 v[106:109], v[158:161], v[214:217], v[106:109]
	v_mfma_f32_16x16x32_bf16 v[94:97], v[150:153], v[222:225], v[94:97]
	v_mfma_f32_16x16x32_bf16 v[90:93], v[158:161], v[222:225], v[90:93]
	v_mfma_f32_16x16x32_bf16 v[78:81], v[150:153], v[230:233], v[78:81]
	v_mfma_f32_16x16x32_bf16 v[74:77], v[158:161], v[230:233], v[74:77]
	v_mfma_f32_16x16x32_bf16 v[118:121], v[186:189], v[202:205], v[118:121]
	v_mfma_f32_16x16x32_bf16 v[114:117], v[194:197], v[202:205], v[114:117]
	v_mfma_f32_16x16x32_bf16 v[102:105], v[186:189], v[210:213], v[102:105]
	v_mfma_f32_16x16x32_bf16 v[98:101], v[194:197], v[210:213], v[98:101]
	v_mfma_f32_16x16x32_bf16 v[86:89], v[186:189], v[218:221], v[86:89]
	v_mfma_f32_16x16x32_bf16 v[82:85], v[194:197], v[218:221], v[82:85]
	v_mfma_f32_16x16x32_bf16 v[70:73], v[186:189], v[226:229], v[70:73]
	v_mfma_f32_16x16x32_bf16 v[66:69], v[194:197], v[226:229], v[66:69]
	v_mfma_f32_16x16x32_bf16 v[118:121], v[190:193], v[206:209], v[118:121]
	v_mfma_f32_16x16x32_bf16 v[114:117], v[198:201], v[206:209], v[114:117]
	v_mfma_f32_16x16x32_bf16 v[102:105], v[190:193], v[214:217], v[102:105]
	v_mfma_f32_16x16x32_bf16 v[98:101], v[198:201], v[214:217], v[98:101]
	v_mfma_f32_16x16x32_bf16 v[86:89], v[190:193], v[222:225], v[86:89]
	v_mfma_f32_16x16x32_bf16 v[82:85], v[198:201], v[222:225], v[82:85]
	v_mfma_f32_16x16x32_bf16 v[70:73], v[190:193], v[230:233], v[70:73]
	v_mfma_f32_16x16x32_bf16 v[66:69], v[198:201], v[230:233], v[66:69]
	s_barrier
; #define PG8_STAGE(bufoff, gbase, off, q) do { \
;         __builtin_amdgcn_global_load_lds((const unsigned*)((const char*)(gbase) + (off)), (LAS unsigned*)(lds + (bufoff) + ldsw), 16, 0, 0); \
;         __builtin_amdgcn_global_load_lds((const unsigned*)((const char*)(gbase) + (q) + (off)), (LAS unsigned*)(lds + (bufoff) + ldsw + 8192), 16, 0, 0); } while (0)
; #define PG8_LDA(dst, b, h) do { _Pragma("unroll") for (int m = 0; m < 4; ++m) _Pragma("unroll") for (int k = 0; k < 2; ++k) dst[m][k] = *(const LAS bf16x8*)(lds + PG8_SA(b, h) + aoff + m * 2048 + k * 1024); } while (0)
; #define PG8_MMA(ai, bj, At, Bt) do { __builtin_amdgcn_s_setprio(1); _Pragma("unroll") for (int m = 0; m < 4; ++m) _Pragma("unroll") for (int n = 0; n < 2; ++n) _Pragma("unroll") for (int k = 0; k < 2; ++k) \
;         acc[ai][bj][m][n] = __builtin_amdgcn_mfma_f32_16x16x32_bf16(Bt[n][k], At[m][k], acc[ai][bj][m][n], 0, 0, 0); __builtin_amdgcn_s_setprio(0); } while (0)
; #define PG8_WAIT_V(n) asm volatile("s_waitcnt vmcnt(" #n ")" ::: "memory")
; #define PG8_WAIT_L(n) asm volatile("s_waitcnt lgkmcnt(" #n ")" ::: "memory")
; #define PG8_BAR __builtin_amdgcn_s_barrier()
; #define PG8_SCHED __builtin_amdgcn_sched_barrier(0)
; template <class Epi, class Sched>
; __device__ __forceinline__ void gemm_phase(LAS unsigned char* lds, const int tid, const Sched& S, const Epi& E) {
;     ...
;             PG8_LDA(At, 1, 1); PG8_STAGE(PG8_SB(1, 0), b3, oB2, qB2); PG8_STAGE(PG8_SB(1, 1), b3 + hB2, oB2, qB2); PG8_STAGE(PG8_SA(1, 0), a3, oA2, qA2);
;             PG8_WAIT_V(8); PG8_WAIT_L(0); PG8_BAR; PG8_MMA(1, 0, At, B0); PG8_MMA(1, 1, At, B1); PG8_BAR; PG8_SCHED;
;         }
	s_setprio 0
	s_add_i32 s6, s10, s47
	s_add_i32 m0, s6, 0xffffff80
	ds_read_b128 v[202:205], v184 offset:49152
	ds_read_b128 v[206:209], v184 offset:50176
	ds_read_b128 v[210:213], v184 offset:51200
	ds_read_b128 v[214:217], v184 offset:52224
	ds_read_b128 v[218:221], v184 offset:53248
	ds_read_b128 v[222:225], v184 offset:54272
	ds_read_b128 v[226:229], v184 offset:55296
	ds_read_b128 v[230:233], v184 offset:56320
	global_load_lds_dwordx4 v0, s[28:29] offset:128
	s_add_i32 m0, s6, 0x1f80
	s_add_i32 s6, s11, s47
	s_ashr_i32 s100, s73, 31
	s_add_u32 s98, s28, s73
	s_addc_u32 s99, s29, s100
	global_load_lds_dwordx4 v0, s[98:99] offset:128
	s_add_i32 m0, s6, 0xffffff80
	s_nop 0
	s_ashr_i32 s101, s19, 31
	s_add_u32 s98, s28, s19
	s_addc_u32 s99, s29, s101
	global_load_lds_dwordx4 v0, s[98:99] offset:128
	s_add_i32 m0, s6, 0x1f80
	s_nop 0
	s_add_u32 s98, s98, s73
	s_addc_u32 s99, s99, s100
	global_load_lds_dwordx4 v0, s[98:99] offset:128
	s_add_i32 m0, s77, 0xffffff80
	s_nop 0
	global_load_lds_dwordx4 v136, vcc offset:128
	s_add_i32 m0, s88, 0xffffff80
	s_nop 0
	s_add_u32 s98, vcc_lo, s64
	s_addc_u32 s99, vcc_hi, s65
	global_load_lds_dwordx4 v136, s[98:99] offset:128
	s_waitcnt vmcnt(8)
	s_waitcnt lgkmcnt(0)
	s_setprio 1
	s_barrier
	v_mfma_f32_16x16x32_bf16 v[62:65], v[140:143], v[202:205], v[62:65]
	v_mfma_f32_16x16x32_bf16 v[58:61], v[154:157], v[202:205], v[58:61]
	v_mfma_f32_16x16x32_bf16 v[46:49], v[140:143], v[210:213], v[46:49]
	v_mfma_f32_16x16x32_bf16 v[42:45], v[154:157], v[210:213], v[42:45]
	v_mfma_f32_16x16x32_bf16 v[30:33], v[140:143], v[218:221], v[30:33]
	v_mfma_f32_16x16x32_bf16 v[26:29], v[154:157], v[218:221], v[26:29]
	v_mfma_f32_16x16x32_bf16 v[14:17], v[140:143], v[226:229], v[14:17]
	v_mfma_f32_16x16x32_bf16 v[10:13], v[154:157], v[226:229], v[10:13]
	v_mfma_f32_16x16x32_bf16 v[62:65], v[150:153], v[206:209], v[62:65]
	v_mfma_f32_16x16x32_bf16 v[58:61], v[158:161], v[206:209], v[58:61]
	v_mfma_f32_16x16x32_bf16 v[46:49], v[150:153], v[214:217], v[46:49]
	v_mfma_f32_16x16x32_bf16 v[42:45], v[158:161], v[214:217], v[42:45]
	v_mfma_f32_16x16x32_bf16 v[30:33], v[150:153], v[222:225], v[30:33]
	v_mfma_f32_16x16x32_bf16 v[26:29], v[158:161], v[222:225], v[26:29]
	v_mfma_f32_16x16x32_bf16 v[14:17], v[150:153], v[230:233], v[14:17]
	v_mfma_f32_16x16x32_bf16 v[10:13], v[158:161], v[230:233], v[10:13]
	v_mfma_f32_16x16x32_bf16 v[54:57], v[186:189], v[202:205], v[54:57]
	v_mfma_f32_16x16x32_bf16 v[50:53], v[194:197], v[202:205], v[50:53]
	v_mfma_f32_16x16x32_bf16 v[38:41], v[186:189], v[210:213], v[38:41]
	v_mfma_f32_16x16x32_bf16 v[34:37], v[194:197], v[210:213], v[34:37]
	v_mfma_f32_16x16x32_bf16 v[22:25], v[186:189], v[218:221], v[22:25]
	v_mfma_f32_16x16x32_bf16 v[18:21], v[194:197], v[218:221], v[18:21]
	v_mfma_f32_16x16x32_bf16 v[6:9], v[186:189], v[226:229], v[6:9]
	v_mfma_f32_16x16x32_bf16 v[2:5], v[194:197], v[226:229], v[2:5]
	v_mfma_f32_16x16x32_bf16 v[54:57], v[190:193], v[206:209], v[54:57]
	v_mfma_f32_16x16x32_bf16 v[50:53], v[198:201], v[206:209], v[50:53]
	v_mfma_f32_16x16x32_bf16 v[38:41], v[190:193], v[214:217], v[38:41]
	v_mfma_f32_16x16x32_bf16 v[34:37], v[198:201], v[214:217], v[34:37]
	v_mfma_f32_16x16x32_bf16 v[22:25], v[190:193], v[222:225], v[22:25]
	v_mfma_f32_16x16x32_bf16 v[18:21], v[198:201], v[222:225], v[18:21]
	v_mfma_f32_16x16x32_bf16 v[6:9], v[190:193], v[230:233], v[6:9]
	v_mfma_f32_16x16x32_bf16 v[2:5], v[198:201], v[230:233], v[2:5]
	s_barrier
	s_setprio 0
	s_cmp_ge_i32 s20, s37
	s_cbranch_scc1 .LBB0_177
	s_mov_b32 s17, s20
	s_branch .LBB0_173
